# D5 sparse attention: gather addressing via scalar base + 32-bit offsets; bias-LUT reads and transposed V fragment reads of each 32-key group issued in batches on otherwise unused VGPRs, lgkmcnt waits
# speedup vs baseline: 1.1486x; 1.0062x over previous
; #define SA_GATHER(GR, SELV) do { _Pragma("unroll") for (int i = 0; i < 8; ++i) { \
;             unsigned sidx = ((SELV)[i >> 1] >> ((i & 1) * 16)) & 0xFFFFu; sidx = sidx == 0xFFFFu ? 0u : sidx; \
;             (GR)[i] = *(const u32x4*)(kg + (size_t)sidx * 128 + r * 8); } } while (0)
; __device__ __forceinline__ void dsa_attn_phase(const Params& p, int j, unsigned char* smem) {
;     ...
;         h16x8 qf[4];
; #pragma unroll
;         for (int kk = 0; kk < 4; ++kk) qf[kk] = *(const h16x8*)(qabs + (size_t)row * 2048 + r * 128 + kk * 32 + q * 8);
;         f32x4 O[8];
; #pragma unroll
;         for (int dt = 0; dt < 8; ++dt) O[dt] = (f32x4){0.f, 0.f, 0.f, 0.f};
;         float mrun = NINF, lrun = 0.f;
;         u32x4 selA = *(const u32x4*)(srow + 8 * q), selB = selA;
;         u32x4 grA[8], grB[8];
;     ...
;         SA_GATHER(grA, selA);
;         if (ng > 1) { selB = *(const u32x4*)(srow + 32 + 8 * q); SA_GATHER(grB, selB); }
.LBB0_95:
	v_ashrrev_i32_e32 v129, 31, v128
	v_lshlrev_b64 v[72:73], 9, v[128:129]
	v_lshl_add_u64 v[74:75], v[134:135], 0, v[72:73]
	global_load_dwordx4 v[120:123], v[74:75], off
	v_and_b32_e32 v0, 0xfffff800, v128
	v_ashrrev_i32_e32 v1, 31, v0
	v_lshlrev_b64 v[46:47], 8, v[0:1]
	v_lshl_add_u64 v[144:145], v[132:133], 0, v[46:47]
	v_lshlrev_b64 v[142:143], 12, v[128:129]
	v_lshl_add_u64 v[44:45], v[130:131], 0, v[142:143]
	v_readfirstlane_b32 s12, v144
	v_readfirstlane_b32 s13, v145
	v_and_b32_e32 v192, 15, v226
	v_lshlrev_b32_e32 v192, 4, v192
	global_load_dwordx4 v[0:3], v[44:45], off
	global_load_dwordx4 v[4:7], v[44:45], off offset:64
	global_load_dwordx4 v[8:11], v[44:45], off offset:128
	v_and_b32_e32 v129, 0x7ff, v128
	s_waitcnt vmcnt(3)
	v_bfe_u32 v48, v120, 0, 11
	v_bfe_u32 v52, v120, 16, 11
	v_bfe_u32 v56, v121, 0, 11
	v_bfe_u32 v60, v121, 16, 11
	v_bfe_u32 v64, v122, 0, 11
	v_bfe_u32 v68, v122, 16, 11
	v_bfe_u32 v76, v123, 0, 11
	v_bfe_u32 v88, v123, 16, 11
	v_lshl_add_u32 v48, v48, 8, v192
	v_lshl_add_u32 v52, v52, 8, v192
	v_lshl_add_u32 v56, v56, 8, v192
	v_lshl_add_u32 v60, v60, 8, v192
	v_lshl_add_u32 v64, v64, 8, v192
	v_lshl_add_u32 v68, v68, 8, v192
	v_lshl_add_u32 v76, v76, 8, v192
	v_lshl_add_u32 v88, v88, 8, v192
	v_mov_b64_e32 v[116:117], v[120:121]
	v_mov_b64_e32 v[118:119], v[122:123]
	global_load_dwordx4 v[44:47], v[44:45], off offset:192
	global_load_dwordx4 v[48:51], v48, s[12:13]
	s_nop 0
	global_load_dwordx4 v[52:55], v52, s[12:13]
	s_nop 0
	global_load_dwordx4 v[56:59], v56, s[12:13]
	s_nop 0
	global_load_dwordx4 v[60:63], v60, s[12:13]
	s_nop 0
	global_load_dwordx4 v[64:67], v64, s[12:13]
	s_nop 0
	global_load_dwordx4 v[68:71], v68, s[12:13]
	s_nop 0
	global_load_dwordx4 v[76:79], v76, s[12:13]
	v_cmp_lt_u32_e32 vcc, 31, v129
	s_nop 0
	global_load_dwordx4 v[88:91], v88, s[12:13]
	s_and_saveexec_b64 s[4:5], vcc
	s_cbranch_execz .LBB0_97
	global_load_dwordx4 v[116:119], v[74:75], off offset:64
	s_waitcnt vmcnt(0)
	v_bfe_u32 v12, v116, 0, 11
	v_bfe_u32 v16, v116, 16, 11
	v_bfe_u32 v20, v117, 0, 11
	v_bfe_u32 v24, v117, 16, 11
	v_bfe_u32 v28, v118, 0, 11
	v_bfe_u32 v32, v118, 16, 11
	v_bfe_u32 v36, v119, 0, 11
	v_bfe_u32 v40, v119, 16, 11
	v_lshl_add_u32 v12, v12, 8, v192
	v_lshl_add_u32 v16, v16, 8, v192
	v_lshl_add_u32 v20, v20, 8, v192
	v_lshl_add_u32 v24, v24, 8, v192
	v_lshl_add_u32 v28, v28, 8, v192
	v_lshl_add_u32 v32, v32, 8, v192
	v_lshl_add_u32 v36, v36, 8, v192
	v_lshl_add_u32 v40, v40, 8, v192
	global_load_dwordx4 v[12:15], v12, s[12:13]
	s_nop 0
	global_load_dwordx4 v[16:19], v16, s[12:13]
	s_nop 0
	global_load_dwordx4 v[20:23], v20, s[12:13]
	s_nop 0
	global_load_dwordx4 v[24:27], v24, s[12:13]
	s_nop 0
	global_load_dwordx4 v[28:31], v28, s[12:13]
	s_nop 0
	global_load_dwordx4 v[32:35], v32, s[12:13]
	s_nop 0
	global_load_dwordx4 v[36:39], v36, s[12:13]
	s_nop 0
	global_load_dwordx4 v[40:43], v40, s[12:13]

.LBB0_98:
	s_or_b64 exec, exec, s[8:9]
	s_waitcnt lgkmcnt(0)
	v_sub_u32_sdwa v224, v129, v116 dst_sel:DWORD dst_unused:UNUSED_PAD src0_sel:DWORD src1_sel:WORD_0
	v_med3_i32 v224, v224, 0, v233
	v_lshl_add_u32 v224, v224, 2, v148
	ds_read_b32 v224, v224
	v_sub_u32_sdwa v225, v129, v116 dst_sel:DWORD dst_unused:UNUSED_PAD src0_sel:DWORD src1_sel:WORD_1
	v_med3_i32 v225, v225, 0, v233
	v_lshl_add_u32 v225, v225, 2, v148
	ds_read_b32 v225, v225
	v_sub_u32_sdwa v246, v129, v117 dst_sel:DWORD dst_unused:UNUSED_PAD src0_sel:DWORD src1_sel:WORD_0
	v_med3_i32 v246, v246, 0, v233
	v_lshl_add_u32 v246, v246, 2, v148
	ds_read_b32 v246, v246
	v_sub_u32_sdwa v247, v129, v117 dst_sel:DWORD dst_unused:UNUSED_PAD src0_sel:DWORD src1_sel:WORD_1
	v_med3_i32 v247, v247, 0, v233
	v_lshl_add_u32 v247, v247, 2, v148
	ds_read_b32 v247, v247
	v_sub_u32_sdwa v193, v129, v118 dst_sel:DWORD dst_unused:UNUSED_PAD src0_sel:DWORD src1_sel:WORD_0
	v_med3_i32 v193, v193, 0, v233
	v_lshl_add_u32 v193, v193, 2, v148
	ds_read_b32 v193, v193
	v_sub_u32_sdwa v194, v129, v118 dst_sel:DWORD dst_unused:UNUSED_PAD src0_sel:DWORD src1_sel:WORD_1
	v_med3_i32 v194, v194, 0, v233
	v_lshl_add_u32 v194, v194, 2, v148
	ds_read_b32 v194, v194
	v_sub_u32_sdwa v195, v129, v119 dst_sel:DWORD dst_unused:UNUSED_PAD src0_sel:DWORD src1_sel:WORD_0
	v_med3_i32 v195, v195, 0, v233
	v_lshl_add_u32 v195, v195, 2, v148
	ds_read_b32 v195, v195
	v_sub_u32_sdwa v248, v129, v119 dst_sel:DWORD dst_unused:UNUSED_PAD src0_sel:DWORD src1_sel:WORD_1
	v_med3_i32 v248, v248, 0, v233
	v_lshl_add_u32 v248, v248, 2, v148
	ds_read_b32 v248, v248
	ds_read_b128 v[124:127], v157 offset:8192
	ds_read_b128 v[182:185], v158 offset:8192
	v_cmp_ne_u32_sdwa vcc, v116, s59 src0_sel:WORD_0 src1_sel:DWORD
	s_mov_b32 s8, 0xff800000
	s_waitcnt lgkmcnt(1)
	v_mfma_f32_16x16x32_f16 v[124:127], v[124:127], v[0:3], 0
	ds_read_b128 v[186:189], v162 offset:8192
	s_waitcnt lgkmcnt(1)
	v_mfma_f32_16x16x32_f16 v[124:127], v[182:185], v[4:7], v[124:127]
	ds_read_b128 v[182:185], v159 offset:8192
	s_waitcnt lgkmcnt(0)
	v_mfma_f32_16x16x32_f16 v[124:127], v[182:185], v[8:11], v[124:127]
	ds_read_b128 v[182:185], v160 offset:8192
	s_waitcnt lgkmcnt(0)
	v_mfma_f32_16x16x32_f16 v[182:185], v[182:185], v[44:47], v[124:127]
	s_nop 4
	ds_read_b128 v[124:127], v161 offset:8192
	s_waitcnt lgkmcnt(0)
	v_mfma_f32_16x16x32_f16 v[124:127], v[124:127], v[0:3], 0
	v_mfma_f32_16x16x32_f16 v[124:127], v[186:189], v[4:7], v[124:127]
	ds_read_b128 v[186:189], v163 offset:8192
	s_waitcnt lgkmcnt(0)
	v_mfma_f32_16x16x32_f16 v[124:127], v[186:189], v[8:11], v[124:127]
	ds_read_b128 v[186:189], v164 offset:8192
	s_waitcnt lgkmcnt(0)
	v_mfma_f32_16x16x32_f16 v[124:127], v[186:189], v[44:47], v[124:127]
	ds_read_b64_tr_b16 v[204:205], v165 offset:8192
	ds_read_b64_tr_b16 v[206:207], v166 offset:8192
	ds_read_b64_tr_b16 v[208:209], v167 offset:8192
	ds_read_b64_tr_b16 v[210:211], v168 offset:8192
	ds_read_b64_tr_b16 v[212:213], v169 offset:8192
	ds_read_b64_tr_b16 v[214:215], v170 offset:8192
	ds_read_b64_tr_b16 v[216:217], v171 offset:8192
	ds_read_b64_tr_b16 v[218:219], v172 offset:8192
	ds_read_b64_tr_b16 v[220:221], v173 offset:8192
	ds_read_b64_tr_b16 v[222:223], v174 offset:8192
	ds_read_b64_tr_b16 v[238:239], v175 offset:8192
	ds_read_b64_tr_b16 v[240:241], v176 offset:8192
	s_nop 3
	v_add_f32_e32 v182, v182, v224
	s_nop 3
	v_cndmask_b32_e32 v182, v234, v182, vcc
	v_cmp_ne_u32_sdwa vcc, v116, s59 src0_sel:WORD_1 src1_sel:DWORD
	v_add_f32_e32 v183, v183, v225
	s_nop 3
	v_cndmask_b32_e32 v116, v234, v183, vcc
	v_cmp_ne_u32_sdwa vcc, v117, s59 src0_sel:WORD_0 src1_sel:DWORD
	v_max3_f32 v183, v182, s8, v116
	v_add_f32_e32 v184, v184, v246
	s_nop 3
	v_cndmask_b32_e32 v184, v234, v184, vcc
	v_cmp_ne_u32_sdwa vcc, v117, s59 src0_sel:WORD_1 src1_sel:DWORD
	v_add_f32_e32 v185, v185, v247
	v_cndmask_b32_e32 v117, v234, v185, vcc
	s_nop 3
	v_cmp_ne_u32_sdwa vcc, v118, s59 src0_sel:WORD_0 src1_sel:DWORD
	v_max3_f32 v183, v183, v184, v117
	v_add_f32_e32 v124, v124, v193
	s_nop 3
	v_cndmask_b32_e32 v124, v234, v124, vcc
	v_cmp_ne_u32_sdwa vcc, v118, s59 src0_sel:WORD_1 src1_sel:DWORD
	v_add_f32_e32 v125, v125, v194
	v_cndmask_b32_e32 v118, v234, v125, vcc
	v_max3_f32 v125, v183, v124, v118
	s_nop 3
	v_cmp_ne_u32_sdwa vcc, v119, s59 src0_sel:WORD_0 src1_sel:DWORD
	v_add_f32_e32 v126, v126, v195
	s_nop 3
	v_cndmask_b32_e32 v126, v234, v126, vcc
	v_cmp_ne_u32_sdwa vcc, v119, s59 src0_sel:WORD_1 src1_sel:DWORD
	v_add_f32_e32 v127, v127, v248
	v_cndmask_b32_e32 v119, v234, v127, vcc
	v_max3_f32 v125, v125, v126, v119
	v_mov_b32_e32 v127, v125
	s_nop 1
	v_permlane16_swap_b32_e32 v125, v127
	v_max_f32_e32 v127, v127, v127
	v_max_f32_e32 v125, v125, v125
	v_max_f32_e32 v125, v125, v127
	v_mov_b32_e32 v127, v125
	s_nop 1
	v_permlane32_swap_b32_e32 v125, v127
	v_max3_f32 v125, v181, v125, v127
	v_cmp_neq_f32_e32 vcc, s8, v125
	s_nop 1
	v_cndmask_b32_e32 v127, 0, v125, vcc
	v_sub_f32_e32 v116, v116, v127
	v_exp_f32_e32 v187, v116
	v_sub_f32_e32 v116, v184, v127
	v_exp_f32_e32 v188, v116
	v_sub_f32_e32 v116, v117, v127
	v_exp_f32_e32 v189, v116
	v_sub_f32_e32 v116, v124, v127
	v_exp_f32_e32 v190, v116
	v_sub_f32_e32 v116, v118, v127
	v_exp_f32_e32 v191, v116
	v_sub_f32_e32 v116, v126, v127
	v_sub_f32_e32 v181, v181, v127
	v_sub_f32_e32 v182, v182, v127
	v_exp_f32_e32 v126, v116
	v_sub_f32_e32 v116, v119, v127
	v_exp_f32_e32 v186, v182
	v_exp_f32_e32 v127, v116
	v_exp_f32_e32 v124, v181
	s_nop 1
	v_cvt_pk_f16_f32 v118, v190, v191
	v_cvt_pk_f16_f32 v119, v126, v127
	v_cvt_pk_f16_f32 v117, v188, v189
	v_cvt_pk_f16_f32 v116, v186, v187
	v_pk_mul_f32 v[110:111], v[110:111], v[124:125] op_sel_hi:[1,0]
	v_pk_mul_f32 v[108:109], v[108:109], v[124:125] op_sel_hi:[1,0]
	v_pk_mul_f32 v[106:107], v[106:107], v[124:125] op_sel_hi:[1,0]
	v_pk_mul_f32 v[104:105], v[104:105], v[124:125] op_sel_hi:[1,0]
	s_waitcnt lgkmcnt(10)
	v_mfma_f32_16x16x32_f16 v[108:111], v[204:207], v[116:119], v[108:111]
	s_nop 1
	v_pk_mul_f32 v[102:103], v[102:103], v[124:125] op_sel_hi:[1,0]
	v_pk_mul_f32 v[100:101], v[100:101], v[124:125] op_sel_hi:[1,0]
	s_waitcnt lgkmcnt(8)
	v_mfma_f32_16x16x32_f16 v[104:107], v[208:211], v[116:119], v[104:107]
	s_nop 1
	v_pk_mul_f32 v[98:99], v[98:99], v[124:125] op_sel_hi:[1,0]
	v_pk_mul_f32 v[96:97], v[96:97], v[124:125] op_sel_hi:[1,0]
	s_waitcnt lgkmcnt(6)
	v_mfma_f32_16x16x32_f16 v[100:103], v[212:215], v[116:119], v[100:103]
	s_nop 1
	v_pk_mul_f32 v[94:95], v[94:95], v[124:125] op_sel_hi:[1,0]
	v_pk_mul_f32 v[92:93], v[92:93], v[124:125] op_sel_hi:[1,0]
	s_waitcnt lgkmcnt(4)
	v_mfma_f32_16x16x32_f16 v[96:99], v[216:219], v[116:119], v[96:99]
	s_nop 1
	v_pk_mul_f32 v[86:87], v[86:87], v[124:125] op_sel_hi:[1,0]
	v_pk_mul_f32 v[84:85], v[84:85], v[124:125] op_sel_hi:[1,0]
	s_waitcnt lgkmcnt(2)
	v_mfma_f32_16x16x32_f16 v[92:95], v[220:223], v[116:119], v[92:95]
	s_nop 1
	v_pk_mul_f32 v[74:75], v[74:75], v[124:125] op_sel_hi:[1,0]
	v_pk_mul_f32 v[72:73], v[72:73], v[124:125] op_sel_hi:[1,0]
	s_waitcnt lgkmcnt(0)
	v_mfma_f32_16x16x32_f16 v[84:87], v[238:241], v[116:119], v[84:87]
	ds_read_b64_tr_b16 v[182:183], v177 offset:8192
	ds_read_b64_tr_b16 v[184:185], v178 offset:8192
	v_pk_mul_f32 v[82:83], v[82:83], v[124:125] op_sel_hi:[1,0]
	v_pk_mul_f32 v[80:81], v[80:81], v[124:125] op_sel_hi:[1,0]
	s_waitcnt lgkmcnt(0)
	v_mfma_f32_16x16x32_f16 v[72:75], v[182:185], v[116:119], v[72:75]
	ds_read_b64_tr_b16 v[182:183], v179 offset:8192
	ds_read_b64_tr_b16 v[184:185], v180 offset:8192
	v_mov_b32_e32 v181, v125
	s_waitcnt lgkmcnt(0)
	v_mfma_f32_16x16x32_f16 v[80:83], v[182:185], v[116:119], v[80:83]
	v_add_f32_e32 v116, 0, v186
	v_add_f32_e32 v116, v187, v116
	v_add_f32_e32 v116, v188, v116
	v_add_f32_e32 v116, v189, v116
	v_add_f32_e32 v116, v190, v116
	v_add_f32_e32 v116, v191, v116
	v_add_f32_e32 v116, v126, v116
	v_add_f32_e32 v116, v127, v116
	v_fmac_f32_e32 v116, v141, v124
	v_mov_b32_e32 v141, v116
	v_mov_b64_e32 v[116:117], v[120:121]
	v_mov_b64_e32 v[118:119], v[122:123]

.LBB0_100:
	s_add_i32 s11, s10, -1
	v_cmp_lt_u32_e32 vcc, s11, v139
	s_waitcnt vmcnt(7)
	ds_write_b128 v149, v[48:51]
	s_waitcnt vmcnt(6)
	ds_write_b128 v150, v[52:55] offset:256
	s_waitcnt vmcnt(5)
	ds_write_b128 v151, v[56:59] offset:512
	s_waitcnt vmcnt(4)
	ds_write_b128 v152, v[60:63] offset:768
	s_waitcnt vmcnt(3)
	ds_write_b128 v153, v[64:67]
	s_waitcnt vmcnt(2)
	ds_write_b128 v154, v[68:71]
	s_waitcnt vmcnt(1)
	ds_write_b128 v155, v[76:79]
	s_waitcnt vmcnt(0)
	ds_write_b128 v156, v[88:91]
	s_and_saveexec_b64 s[6:7], vcc
	s_cbranch_execz .LBB0_102
	global_load_dwordx4 v[112:115], v[146:147], off offset:-64
	s_waitcnt vmcnt(0)
	v_bfe_u32 v48, v112, 0, 11
	v_bfe_u32 v52, v112, 16, 11
	v_bfe_u32 v56, v113, 0, 11
	v_bfe_u32 v60, v113, 16, 11
	v_bfe_u32 v64, v114, 0, 11
	v_bfe_u32 v68, v114, 16, 11
	v_bfe_u32 v76, v115, 0, 11
	v_bfe_u32 v88, v115, 16, 11
	v_lshl_add_u32 v48, v48, 8, v192
	v_lshl_add_u32 v52, v52, 8, v192
	v_lshl_add_u32 v56, v56, 8, v192
	v_lshl_add_u32 v60, v60, 8, v192
	v_lshl_add_u32 v64, v64, 8, v192
	v_lshl_add_u32 v68, v68, 8, v192
	v_lshl_add_u32 v76, v76, 8, v192
	v_lshl_add_u32 v88, v88, 8, v192
	global_load_dwordx4 v[48:51], v48, s[12:13]
	s_nop 0
	global_load_dwordx4 v[52:55], v52, s[12:13]
	s_nop 0
	global_load_dwordx4 v[56:59], v56, s[12:13]
	s_nop 0
	global_load_dwordx4 v[60:63], v60, s[12:13]
	s_nop 0
	global_load_dwordx4 v[64:67], v64, s[12:13]
	s_nop 0
	global_load_dwordx4 v[68:71], v68, s[12:13]
	s_nop 0
	global_load_dwordx4 v[76:79], v76, s[12:13]
	s_nop 0
	global_load_dwordx4 v[88:91], v88, s[12:13]
.LBB0_102:
	s_or_b64 exec, exec, s[6:7]
	s_waitcnt lgkmcnt(0)
	v_sub_u32_sdwa v224, v129, v120 dst_sel:DWORD dst_unused:UNUSED_PAD src0_sel:DWORD src1_sel:WORD_0
	v_med3_i32 v224, v224, 0, v233
	v_lshl_add_u32 v224, v224, 2, v148
	ds_read_b32 v224, v224
	v_sub_u32_sdwa v225, v129, v120 dst_sel:DWORD dst_unused:UNUSED_PAD src0_sel:DWORD src1_sel:WORD_1
	v_med3_i32 v225, v225, 0, v233
	v_lshl_add_u32 v225, v225, 2, v148
	ds_read_b32 v225, v225
	v_sub_u32_sdwa v246, v129, v121 dst_sel:DWORD dst_unused:UNUSED_PAD src0_sel:DWORD src1_sel:WORD_0
	v_med3_i32 v246, v246, 0, v233
	v_lshl_add_u32 v246, v246, 2, v148
	ds_read_b32 v246, v246
	v_sub_u32_sdwa v247, v129, v121 dst_sel:DWORD dst_unused:UNUSED_PAD src0_sel:DWORD src1_sel:WORD_1
	v_med3_i32 v247, v247, 0, v233
	v_lshl_add_u32 v247, v247, 2, v148
	ds_read_b32 v247, v247
	v_sub_u32_sdwa v193, v129, v122 dst_sel:DWORD dst_unused:UNUSED_PAD src0_sel:DWORD src1_sel:WORD_0
	v_med3_i32 v193, v193, 0, v233
	v_lshl_add_u32 v193, v193, 2, v148
	ds_read_b32 v193, v193
	v_sub_u32_sdwa v194, v129, v122 dst_sel:DWORD dst_unused:UNUSED_PAD src0_sel:DWORD src1_sel:WORD_1
	v_med3_i32 v194, v194, 0, v233
	v_lshl_add_u32 v194, v194, 2, v148
	ds_read_b32 v194, v194
	v_sub_u32_sdwa v195, v129, v123 dst_sel:DWORD dst_unused:UNUSED_PAD src0_sel:DWORD src1_sel:WORD_0
	v_med3_i32 v195, v195, 0, v233
	v_lshl_add_u32 v195, v195, 2, v148
	ds_read_b32 v195, v195
	v_sub_u32_sdwa v248, v129, v123 dst_sel:DWORD dst_unused:UNUSED_PAD src0_sel:DWORD src1_sel:WORD_1
	v_med3_i32 v248, v248, 0, v233
	v_lshl_add_u32 v248, v248, 2, v148
	ds_read_b32 v248, v248
	ds_read_b128 v[124:127], v157
	ds_read_b128 v[184:187], v158
	ds_read_b128 v[188:191], v162
	s_nop 5
	s_waitcnt lgkmcnt(2)
	v_mfma_f32_16x16x32_f16 v[124:127], v[124:127], v[0:3], 0
	s_nop 0
	v_cmp_ne_u32_sdwa vcc, v120, s59 src0_sel:WORD_0 src1_sel:DWORD
	s_mov_b32 s6, 0xff800000
	s_waitcnt lgkmcnt(1)
	v_mfma_f32_16x16x32_f16 v[124:127], v[184:187], v[4:7], v[124:127]
	ds_read_b128 v[184:187], v159
	s_nop 0
	s_waitcnt lgkmcnt(0)
	v_mfma_f32_16x16x32_f16 v[124:127], v[184:187], v[8:11], v[124:127]
	ds_read_b128 v[184:187], v160
	s_waitcnt lgkmcnt(0)
	v_mfma_f32_16x16x32_f16 v[184:187], v[184:187], v[44:47], v[124:127]
	s_nop 4
	ds_read_b128 v[124:127], v161
	s_nop 1
	v_add_f32_e32 v141, v184, v224
	s_nop 3
	s_waitcnt lgkmcnt(0)
	v_mfma_f32_16x16x32_f16 v[124:127], v[124:127], v[0:3], 0
	v_add_f32_e32 v181, v185, v225
	s_nop 1
	v_mfma_f32_16x16x32_f16 v[124:127], v[188:191], v[4:7], v[124:127]
	ds_read_b128 v[188:191], v163
	s_nop 1
	v_cndmask_b32_e32 v141, v234, v141, vcc
	v_cmp_ne_u32_sdwa vcc, v120, s59 src0_sel:WORD_1 src1_sel:DWORD
	s_waitcnt lgkmcnt(0)
	v_mfma_f32_16x16x32_f16 v[124:127], v[188:191], v[8:11], v[124:127]
	ds_read_b128 v[188:191], v164
	v_cndmask_b32_e32 v120, v234, v181, vcc
	v_add_f32_e32 v184, v186, v246
	v_cmp_ne_u32_sdwa vcc, v121, s59 src0_sel:WORD_0 src1_sel:DWORD
	v_add_f32_e32 v185, v187, v247
	v_max3_f32 v181, v141, s6, v120
	v_cndmask_b32_e32 v184, v234, v184, vcc
	v_cmp_ne_u32_sdwa vcc, v121, s59 src0_sel:WORD_1 src1_sel:DWORD
	s_nop 1
	v_cndmask_b32_e32 v121, v234, v185, vcc
	s_nop 3
	s_waitcnt lgkmcnt(0)
; #define SA_GATHER(GR, SELV) do { _Pragma("unroll") for (int i = 0; i < 8; ++i) { \
;             unsigned sidx = ((SELV)[i >> 1] >> ((i & 1) * 16)) & 0xFFFFu; sidx = sidx == 0xFFFFu ? 0u : sidx; \
;             (GR)[i] = *(const u32x4*)(kg + (size_t)sidx * 128 + r * 8); } } while (0)
; __device__ __forceinline__ void dsa_attn_phase(const Params& p, int j, unsigned char* smem) {
;     ...
;         SA_GATHER(grA, selA);
;         if (ng > 1) { selB = *(const u32x4*)(srow + 32 + 8 * q); SA_GATHER(grB, selB); }
;         for (int g = 0; g < ng; g += 2) {
;             SA_GROUP(grA, selA, g);
;             if (g + 1 < ng) SA_GROUP(grB, selB, g + 1);
	v_mfma_f32_16x16x32_f16 v[124:127], v[188:191], v[44:47], v[124:127]
	ds_read_b64_tr_b16 v[204:205], v165
	ds_read_b64_tr_b16 v[206:207], v166
	ds_read_b64_tr_b16 v[208:209], v167
	ds_read_b64_tr_b16 v[210:211], v168
	ds_read_b64_tr_b16 v[212:213], v169
	ds_read_b64_tr_b16 v[214:215], v170
	ds_read_b64_tr_b16 v[216:217], v171
	ds_read_b64_tr_b16 v[218:219], v172
	ds_read_b64_tr_b16 v[220:221], v173
	ds_read_b64_tr_b16 v[222:223], v174
	ds_read_b64_tr_b16 v[238:239], v175
	ds_read_b64_tr_b16 v[240:241], v176
	v_cmp_ne_u32_sdwa vcc, v122, s59 src0_sel:WORD_0 src1_sel:DWORD
	v_max3_f32 v181, v181, v184, v121
	s_nop 4
	v_add_f32_e32 v124, v124, v193
	s_nop 3
	v_cndmask_b32_e32 v124, v234, v124, vcc
	v_cmp_ne_u32_sdwa vcc, v122, s59 src0_sel:WORD_1 src1_sel:DWORD
	v_add_f32_e32 v125, v125, v194
	v_cndmask_b32_e32 v122, v234, v125, vcc
	v_max3_f32 v125, v181, v124, v122
	s_nop 3
	v_cmp_ne_u32_sdwa vcc, v123, s59 src0_sel:WORD_0 src1_sel:DWORD
	v_add_f32_e32 v126, v126, v195
	s_nop 3
	v_cndmask_b32_e32 v126, v234, v126, vcc
	v_cmp_ne_u32_sdwa vcc, v123, s59 src0_sel:WORD_1 src1_sel:DWORD
	v_add_f32_e32 v127, v127, v248
	v_cndmask_b32_e32 v123, v234, v127, vcc
	v_max3_f32 v125, v125, v126, v123
	v_mov_b32_e32 v127, v125
	s_nop 1
	v_permlane16_swap_b32_e32 v125, v127
	v_max_f32_e32 v127, v127, v127
	v_max_f32_e32 v125, v125, v125
	v_max_f32_e32 v125, v125, v127
	v_mov_b32_e32 v127, v125
	s_nop 1
	v_permlane32_swap_b32_e32 v125, v127
	v_max3_f32 v181, v183, v125, v127
	v_cmp_neq_f32_e32 vcc, s6, v181
	s_add_i32 s6, s10, -2
	s_nop 0
	v_cndmask_b32_e32 v125, 0, v181, vcc
	v_sub_f32_e32 v120, v120, v125
	v_sub_f32_e32 v127, v183, v125
	v_exp_f32_e32 v183, v120
	v_sub_f32_e32 v120, v184, v125
	v_exp_f32_e32 v188, v120
	v_sub_f32_e32 v120, v121, v125
	v_exp_f32_e32 v189, v120
	v_sub_f32_e32 v120, v124, v125
	v_exp_f32_e32 v190, v120
	v_sub_f32_e32 v120, v122, v125
	v_exp_f32_e32 v191, v120
	v_sub_f32_e32 v120, v126, v125
	v_sub_f32_e32 v141, v141, v125
	v_exp_f32_e32 v126, v120
	v_sub_f32_e32 v120, v123, v125
	v_exp_f32_e32 v141, v141
	v_exp_f32_e32 v125, v120
	v_exp_f32_e32 v124, v127
	s_nop 1
	v_cvt_pk_f16_f32 v122, v190, v191
	v_cvt_pk_f16_f32 v123, v126, v125
	v_cvt_pk_f16_f32 v121, v188, v189
	v_cvt_pk_f16_f32 v120, v141, v183
	v_pk_mul_f32 v[110:111], v[110:111], v[124:125] op_sel_hi:[1,0]
	v_pk_mul_f32 v[108:109], v[108:109], v[124:125] op_sel_hi:[1,0]
	v_pk_mul_f32 v[106:107], v[106:107], v[124:125] op_sel_hi:[1,0]
	v_pk_mul_f32 v[104:105], v[104:105], v[124:125] op_sel_hi:[1,0]
	s_waitcnt lgkmcnt(10)
	v_mfma_f32_16x16x32_f16 v[108:111], v[204:207], v[120:123], v[108:111]
	s_nop 1
	v_pk_mul_f32 v[102:103], v[102:103], v[124:125] op_sel_hi:[1,0]
	v_pk_mul_f32 v[100:101], v[100:101], v[124:125] op_sel_hi:[1,0]
	s_waitcnt lgkmcnt(8)
	v_mfma_f32_16x16x32_f16 v[104:107], v[208:211], v[120:123], v[104:107]
	s_nop 1
	v_pk_mul_f32 v[98:99], v[98:99], v[124:125] op_sel_hi:[1,0]
	v_pk_mul_f32 v[96:97], v[96:97], v[124:125] op_sel_hi:[1,0]
	s_waitcnt lgkmcnt(6)
	v_mfma_f32_16x16x32_f16 v[100:103], v[212:215], v[120:123], v[100:103]
	s_nop 1
	v_pk_mul_f32 v[94:95], v[94:95], v[124:125] op_sel_hi:[1,0]
	v_pk_mul_f32 v[92:93], v[92:93], v[124:125] op_sel_hi:[1,0]
	s_waitcnt lgkmcnt(4)
	v_mfma_f32_16x16x32_f16 v[96:99], v[216:219], v[120:123], v[96:99]
	s_nop 1
	v_pk_mul_f32 v[86:87], v[86:87], v[124:125] op_sel_hi:[1,0]
	v_pk_mul_f32 v[84:85], v[84:85], v[124:125] op_sel_hi:[1,0]
	s_waitcnt lgkmcnt(2)
	v_mfma_f32_16x16x32_f16 v[92:95], v[220:223], v[120:123], v[92:95]
	s_nop 1
	v_pk_mul_f32 v[74:75], v[74:75], v[124:125] op_sel_hi:[1,0]
	v_pk_mul_f32 v[72:73], v[72:73], v[124:125] op_sel_hi:[1,0]
	s_waitcnt lgkmcnt(0)
	v_mfma_f32_16x16x32_f16 v[84:87], v[238:241], v[120:123], v[84:87]
	ds_read_b64_tr_b16 v[184:185], v177
	ds_read_b64_tr_b16 v[186:187], v178
	v_pk_mul_f32 v[82:83], v[82:83], v[124:125] op_sel_hi:[1,0]
	v_pk_mul_f32 v[80:81], v[80:81], v[124:125] op_sel_hi:[1,0]
	s_waitcnt lgkmcnt(0)
	v_mfma_f32_16x16x32_f16 v[72:75], v[184:187], v[120:123], v[72:75]
	ds_read_b64_tr_b16 v[184:185], v179
	ds_read_b64_tr_b16 v[186:187], v180
	v_cmp_lt_u32_e32 vcc, s6, v139
	s_waitcnt lgkmcnt(0)
	v_mfma_f32_16x16x32_f16 v[80:83], v[184:187], v[120:123], v[80:83]
	v_add_f32_e32 v120, 0, v141
	v_add_f32_e32 v120, v183, v120
	v_add_f32_e32 v120, v188, v120
	v_add_f32_e32 v120, v189, v120
	v_add_f32_e32 v120, v190, v120
	v_add_f32_e32 v120, v191, v120
	v_add_f32_e32 v120, v126, v120
	v_add_f32_e32 v141, v125, v120
	v_fmac_f32_e32 v141, v182, v124
	s_and_saveexec_b64 s[6:7], vcc
	s_cbranch_execz .LBB0_99
	v_mov_b64_e32 v[122:123], v[118:119]
	v_cmp_lt_u32_e32 vcc, s10, v139
	v_mov_b64_e32 v[120:121], v[116:117]
	ds_write_b128 v149, v[12:15] offset:8192
	ds_write_b128 v150, v[16:19] offset:8448
	ds_write_b128 v151, v[20:23] offset:8704
	ds_write_b128 v152, v[24:27] offset:8960
	ds_write_b128 v153, v[28:31] offset:8192
	ds_write_b128 v154, v[32:35] offset:8192
	ds_write_b128 v155, v[36:39] offset:8192
	ds_write_b128 v156, v[40:43] offset:8192
	s_and_saveexec_b64 s[8:9], vcc
	s_cbranch_execz .LBB0_98
	global_load_dwordx4 v[120:123], v[146:147], off
	s_waitcnt vmcnt(0)
	v_bfe_u32 v12, v120, 0, 11
	v_bfe_u32 v16, v120, 16, 11
	v_bfe_u32 v20, v121, 0, 11
	v_bfe_u32 v24, v121, 16, 11
	v_bfe_u32 v28, v122, 0, 11
	v_bfe_u32 v32, v122, 16, 11
	v_bfe_u32 v36, v123, 0, 11
	v_bfe_u32 v40, v123, 16, 11
	v_lshl_add_u32 v12, v12, 8, v192
	v_lshl_add_u32 v16, v16, 8, v192
	v_lshl_add_u32 v20, v20, 8, v192
	v_lshl_add_u32 v24, v24, 8, v192
	v_lshl_add_u32 v28, v28, 8, v192
	v_lshl_add_u32 v32, v32, 8, v192
	v_lshl_add_u32 v36, v36, 8, v192
	v_lshl_add_u32 v40, v40, 8, v192
	global_load_dwordx4 v[12:15], v12, s[12:13]
	s_nop 0
	global_load_dwordx4 v[16:19], v16, s[12:13]
	s_nop 0
	global_load_dwordx4 v[20:23], v20, s[12:13]
	s_nop 0
	global_load_dwordx4 v[24:27], v24, s[12:13]
	s_nop 0
	global_load_dwordx4 v[28:31], v28, s[12:13]
	s_nop 0
	global_load_dwordx4 v[32:35], v32, s[12:13]
	s_nop 0
	global_load_dwordx4 v[36:39], v36, s[12:13]
	s_nop 0
	global_load_dwordx4 v[40:43], v40, s[12:13]
	s_branch .LBB0_98
